# NSA branch loops, non-edge key blocks: scores of keys 0-31 and 32-63 processed as two half-blocks so the exp/sum/pack VALU work of one half runs under the QK / PV MFMAs of the other half (same math, f
# baseline (speedup 1.0000x reference)
.LBB0_121:
	s_nop 7
	v_exp_f32_e32 v196, v48
	s_nop 1
	v_exp_f32_e32 v210, v32
	v_exp_f32_e32 v160, v49
	v_exp_f32_e32 v156, v33
	v_exp_f32_e32 v211, v34
	v_add_f32_e32 v157, v210, v196
	v_exp_f32_e32 v48, v35
	v_pk_add_f32 v[32:33], v[156:157], v[160:161]
	v_exp_f32_e32 v157, v50
	v_pk_add_f32 v[206:207], v[32:33], v[32:33] op_sel_hi:[0,1]
	v_exp_f32_e32 v206, v51
	v_exp_f32_e32 v50, v37
	v_add_f32_e32 v49, v211, v157
	v_pk_add_f32 v[32:33], v[48:49], v[206:207]
	s_nop 0
	v_pk_add_f32 v[244:245], v[32:33], v[32:33] op_sel_hi:[0,1]
	v_exp_f32_e32 v49, v52
	v_exp_f32_e32 v207, v36
	v_exp_f32_e32 v244, v53
	v_exp_f32_e32 v52, v39
	v_add_f32_e32 v51, v207, v49
	v_pk_add_f32 v[32:33], v[50:51], v[244:245]
	v_exp_f32_e32 v51, v54
	v_pk_add_f32 v[246:247], v[32:33], v[32:33] op_sel_hi:[0,1]
	v_exp_f32_e32 v245, v38
	v_exp_f32_e32 v246, v55
	v_add_f32_e32 v53, v245, v51
	v_pk_add_f32 v[32:33], v[52:53], v[246:247]
	v_exp_f32_e32 v53, v56
	v_pk_add_f32 v[54:55], v[32:33], v[32:33] op_sel_hi:[0,1]
	v_exp_f32_e32 v247, v40
	v_exp_f32_e32 v54, v57
	v_exp_f32_e32 v32, v41
	v_add_f32_e32 v33, v247, v53
	v_pk_add_f32 v[34:35], v[32:33], v[54:55]
	s_nop 0
	v_pk_add_f32 v[248:249], v[34:35], v[34:35] op_sel_hi:[0,1]
	v_exp_f32_e32 v33, v58
	v_exp_f32_e32 v55, v42
	v_exp_f32_e32 v248, v59
	v_exp_f32_e32 v34, v43
	v_cvt_pk_bf16_f32 v42, v49, v244
	v_add_f32_e32 v35, v55, v33
	v_cvt_pk_bf16_f32 v43, v51, v246
	v_pk_add_f32 v[36:37], v[34:35], v[248:249]
	v_exp_f32_e32 v35, v60
	v_pk_add_f32 v[250:251], v[36:37], v[36:37] op_sel_hi:[0,1]
	v_exp_f32_e32 v249, v44
	v_exp_f32_e32 v250, v61
	v_exp_f32_e32 v36, v45
	v_add_u32_e32 v49, 0x7000, v243
	v_add_f32_e32 v37, v249, v35
	v_cvt_pk_bf16_f32 v32, v247, v32
	v_pk_add_f32 v[38:39], v[36:37], v[250:251]
	v_exp_f32_e32 v37, v62
	v_pk_add_f32 v[60:61], v[38:39], v[38:39] op_sel_hi:[0,1]
	v_exp_f32_e32 v62, v46
	v_exp_f32_e32 v60, v63
	v_exp_f32_e32 v38, v47
	v_add_f32_e32 v39, v62, v37
	v_pk_add_f32 v[40:41], v[38:39], v[60:61]
	s_nop 0
	v_add_f32_e32 v39, v40, v41
	v_add_f32_e32 v115, v115, v39
	v_add_u32_e32 v39, 0x6000, v243
	ds_read2_b64 v[44:47], v39 offset0:128 offset1:130
	ds_read2_b64 v[56:59], v39 offset0:132 offset1:134
	v_cvt_pk_bf16_f32 v40, v196, v160
	v_cvt_pk_bf16_f32 v41, v157, v206
	s_waitcnt lgkmcnt(1)
	s_nop 0
	v_mfma_f32_32x32x16_bf16 v[0:15], v[44:47], v[40:43], v[0:15]
	ds_read2_b64 v[44:47], v49 offset0:160 offset1:162
	s_waitcnt lgkmcnt(0)
	v_mfma_f32_32x32x16_bf16 v[16:31], v[44:47], v[40:43], v[16:31]
	ds_read2_b64 v[44:47], v49 offset0:164 offset1:166
	v_cvt_pk_bf16_f32 v40, v53, v54
	v_cvt_pk_bf16_f32 v41, v33, v248
	v_cvt_pk_bf16_f32 v42, v35, v250
	v_cvt_pk_bf16_f32 v43, v37, v60
	v_cvt_pk_bf16_f32 v33, v55, v34
	v_cvt_pk_bf16_f32 v34, v249, v36
	s_waitcnt lgkmcnt(0)
	v_mfma_f32_32x32x16_bf16 v[16:31], v[44:47], v[40:43], v[16:31]
	ds_read2_b64 v[44:47], v39 offset0:136 offset1:138
	v_cvt_pk_bf16_f32 v35, v62, v38
	ds_read2_b64 v[36:39], v39 offset0:140 offset1:142
	v_mfma_f32_32x32x16_bf16 v[0:15], v[56:59], v[40:43], v[0:15]
	v_cvt_pk_bf16_f32 v40, v210, v156
	v_cvt_pk_bf16_f32 v41, v211, v48
	v_cvt_pk_bf16_f32 v42, v207, v50
	v_cvt_pk_bf16_f32 v43, v245, v52
	s_waitcnt lgkmcnt(1)
	s_nop 0
	v_mfma_f32_32x32x16_bf16 v[0:15], v[44:47], v[40:43], v[0:15]
	ds_read2_b64 v[44:47], v49 offset0:168 offset1:170
	s_waitcnt lgkmcnt(1)
	v_mfma_f32_32x32x16_bf16 v[0:15], v[36:39], v[32:35], v[0:15]
	ds_read2_b64 v[36:39], v49 offset0:172 offset1:174
	s_waitcnt lgkmcnt(1)
	v_mfma_f32_32x32x16_bf16 v[16:31], v[44:47], v[40:43], v[16:31]
	s_waitcnt lgkmcnt(0)
	v_mfma_f32_32x32x16_bf16 v[16:31], v[36:39], v[32:35], v[16:31]
	s_branch .LBB0_122
.Lnsa_fast_B:
	ds_read_b128 v[244:247], v242 offset:16384
	ds_read_b128 v[248:251], v242 offset:16416
	v_and_b32_e32 v32, s10, v234
	v_cmp_ne_u32_e32 vcc, 0, v32
	v_add_u32_e32 v210, 0x6000, v243
	v_add_u32_e32 v211, 0x7000, v243
	v_cndmask_b32_e64 v32, v208, -v232, vcc
	v_mov_b32_e32 v33, v32
	v_mov_b32_e32 v34, v32
	v_mov_b32_e32 v35, v32
	v_mov_b32_e32 v36, v32
	v_mov_b32_e32 v37, v32
	v_mov_b32_e32 v38, v32
	v_mov_b32_e32 v39, v32
	v_mov_b32_e32 v40, v32
	v_mov_b32_e32 v41, v32
	v_mov_b32_e32 v42, v32
	v_mov_b32_e32 v43, v32
	v_mov_b32_e32 v44, v32
	v_mov_b32_e32 v45, v32
	v_mov_b32_e32 v46, v32
	v_mov_b32_e32 v47, v32
	s_waitcnt lgkmcnt(1)
	v_mfma_f32_32x32x16_bf16 v[48:63], v[244:247], v[64:67], v[32:47]
	ds_read_b128 v[244:247], v242 offset:16448
	s_waitcnt lgkmcnt(1)
	v_mfma_f32_32x32x16_bf16 v[48:63], v[248:251], v[68:71], v[48:63]
	ds_read_b128 v[248:251], v242 offset:16480
	s_waitcnt lgkmcnt(1)
	v_mfma_f32_32x32x16_bf16 v[48:63], v[244:247], v[72:75], v[48:63]
	ds_read_b128 v[244:247], v242 offset:20992
	s_waitcnt lgkmcnt(1)
	v_mfma_f32_32x32x16_bf16 v[48:63], v[248:251], v[76:79], v[48:63]
	ds_read_b128 v[248:251], v242 offset:21024
	s_waitcnt lgkmcnt(1)
	v_mfma_f32_32x32x16_bf16 v[32:47], v[244:247], v[64:67], v[32:47]
	ds_read_b128 v[244:247], v242 offset:21056
	s_nop 7
	s_nop 7
	v_exp_f32_e32 v48, v48
	v_exp_f32_e32 v49, v49
	v_exp_f32_e32 v50, v50
	v_exp_f32_e32 v51, v51
	s_waitcnt lgkmcnt(1)
	v_mfma_f32_32x32x16_bf16 v[32:47], v[248:251], v[68:71], v[32:47]
	ds_read_b128 v[248:251], v242 offset:21088
	v_exp_f32_e32 v52, v52
	v_exp_f32_e32 v53, v53
	v_exp_f32_e32 v54, v54
	v_exp_f32_e32 v55, v55
	v_add_f32_e32 v156, v48, v49
	v_add_f32_e32 v157, v50, v51
	s_waitcnt lgkmcnt(1)
	v_mfma_f32_32x32x16_bf16 v[32:47], v[244:247], v[72:75], v[32:47]
	v_exp_f32_e32 v56, v56
	v_exp_f32_e32 v57, v57
	v_exp_f32_e32 v58, v58
	v_exp_f32_e32 v59, v59
	v_add_f32_e32 v160, v52, v53
	v_add_f32_e32 v196, v54, v55
	s_waitcnt lgkmcnt(0)
	v_mfma_f32_32x32x16_bf16 v[32:47], v[248:251], v[76:79], v[32:47]
	ds_read2_b64 v[244:247], v210 offset0:132 offset1:134
	ds_read2_b64 v[248:251], v211 offset0:164 offset1:166
	v_exp_f32_e32 v60, v60
	v_exp_f32_e32 v61, v61
	v_exp_f32_e32 v62, v62
	v_exp_f32_e32 v63, v63
	v_add_f32_e32 v156, v156, v157
	v_add_f32_e32 v160, v160, v196
	v_add_f32_e32 v157, v56, v57
	v_add_f32_e32 v196, v58, v59
	v_add_f32_e32 v156, v156, v160
	v_add_f32_e32 v157, v157, v196
	v_add_f32_e32 v160, v60, v61
	v_add_f32_e32 v196, v62, v63
	v_add_f32_e32 v160, v160, v196
	v_add_f32_e32 v157, v157, v160
	v_add_f32_e32 v156, v156, v157
	v_add_f32_e32 v115, v115, v156
	v_cvt_pk_bf16_f32 v48, v48, v49
	v_cvt_pk_bf16_f32 v49, v50, v51
	v_cvt_pk_bf16_f32 v50, v52, v53
	v_cvt_pk_bf16_f32 v51, v54, v55
	v_cvt_pk_bf16_f32 v52, v56, v57
	v_cvt_pk_bf16_f32 v53, v58, v59
	v_cvt_pk_bf16_f32 v54, v60, v61
	v_cvt_pk_bf16_f32 v55, v62, v63
	ds_read2_b64 v[56:59], v210 offset0:128 offset1:130
	ds_read2_b64 v[60:63], v211 offset0:160 offset1:162
	s_waitcnt lgkmcnt(3)
	v_mfma_f32_32x32x16_bf16 v[0:15], v[244:247], v[52:55], v[0:15]
	ds_read2_b64 v[244:247], v210 offset0:136 offset1:138
	v_exp_f32_e32 v32, v32
	v_exp_f32_e32 v33, v33
	v_exp_f32_e32 v34, v34
	v_exp_f32_e32 v35, v35
	s_waitcnt lgkmcnt(3)
	v_mfma_f32_32x32x16_bf16 v[16:31], v[248:251], v[52:55], v[16:31]
	ds_read2_b64 v[248:251], v211 offset0:168 offset1:170
	v_exp_f32_e32 v36, v36
	v_exp_f32_e32 v37, v37
	v_exp_f32_e32 v38, v38
	v_exp_f32_e32 v39, v39
	v_add_f32_e32 v156, v32, v33
	v_add_f32_e32 v157, v34, v35
	s_waitcnt lgkmcnt(3)
	v_mfma_f32_32x32x16_bf16 v[0:15], v[56:59], v[48:51], v[0:15]
	ds_read2_b64 v[56:59], v210 offset0:140 offset1:142
	v_exp_f32_e32 v40, v40
	v_exp_f32_e32 v41, v41
	v_exp_f32_e32 v42, v42
	v_exp_f32_e32 v43, v43
	v_add_f32_e32 v160, v36, v37
	v_add_f32_e32 v196, v38, v39
	s_waitcnt lgkmcnt(3)
	v_mfma_f32_32x32x16_bf16 v[16:31], v[60:63], v[48:51], v[16:31]
	ds_read2_b64 v[60:63], v211 offset0:172 offset1:174
	v_exp_f32_e32 v44, v44
	v_exp_f32_e32 v45, v45
	v_exp_f32_e32 v46, v46
	v_exp_f32_e32 v47, v47
	v_add_f32_e32 v156, v156, v157
	v_add_f32_e32 v160, v160, v196
	v_add_f32_e32 v157, v40, v41
	v_add_f32_e32 v196, v42, v43
	v_add_f32_e32 v156, v156, v160
	v_add_f32_e32 v157, v157, v196
	v_add_f32_e32 v160, v44, v45
	v_add_f32_e32 v196, v46, v47
	v_add_f32_e32 v160, v160, v196
	v_add_f32_e32 v157, v157, v160
	v_add_f32_e32 v156, v156, v157
	v_add_f32_e32 v115, v115, v156
	v_cvt_pk_bf16_f32 v32, v32, v33
	v_cvt_pk_bf16_f32 v33, v34, v35
	v_cvt_pk_bf16_f32 v34, v36, v37
	v_cvt_pk_bf16_f32 v35, v38, v39
	v_cvt_pk_bf16_f32 v36, v40, v41
	v_cvt_pk_bf16_f32 v37, v42, v43
	v_cvt_pk_bf16_f32 v38, v44, v45
	v_cvt_pk_bf16_f32 v39, v46, v47
	s_waitcnt lgkmcnt(3)
	s_nop 0
	v_mfma_f32_32x32x16_bf16 v[0:15], v[244:247], v[32:35], v[0:15]
	s_waitcnt lgkmcnt(2)
	v_mfma_f32_32x32x16_bf16 v[16:31], v[248:251], v[32:35], v[16:31]
	s_waitcnt lgkmcnt(1)
	v_mfma_f32_32x32x16_bf16 v[0:15], v[56:59], v[36:39], v[0:15]
	s_waitcnt lgkmcnt(0)
	v_mfma_f32_32x32x16_bf16 v[16:31], v[60:63], v[36:39], v[16:31]

.LBB0_123:
	s_ff1_i32_b32 s14, s12
	v_sub_co_u32_e64 v32, s[94:95], s12, 1
	s_lshl_b32 s15, s14, 6
	s_and_b64 s[78:79], s[94:95], exec
	s_cselect_b32 s15, 0, s15
	v_readfirstlane_b32 s13, v32
	v_add_u32_e32 v32, s15, v231
	v_ashrrev_i32_e32 v33, 31, v32
	s_waitcnt vmcnt(3)
	ds_write_b128 v236, v[80:83] offset:16384
	s_waitcnt vmcnt(2)
	ds_write2_b64 v237, v[84:85], v[86:87] offset1:1
	v_lshlrev_b64 v[32:33], 11, v[32:33]
	s_waitcnt lgkmcnt(0)
	s_barrier
	v_lshl_add_u64 v[32:33], v[152:153], 0, v[32:33]
	s_lshl_b32 s92, s15, 7
	global_load_dwordx4 v[80:83], v[32:33], off
	v_lshl_add_u64 v[32:33], v[154:155], 0, s[92:93]
	global_load_dwordx4 v[84:87], v[32:33], off
	s_lshl_b32 s15, 1, s10
	v_and_b32_e32 v32, s15, v235
	v_cmp_ne_u32_e32 vcc, 0, v32
	s_and_saveexec_b64 s[84:85], vcc
	s_cbranch_execz .LBB0_127
	s_cmp_lg_u32 s10, s89
	s_cselect_b64 s[98:99], -1, 0
	s_cmp_lg_u32 s10, s8
	s_cselect_b64 vcc, -1, 0
	s_and_b64 s[98:99], s[98:99], vcc
	s_cbranch_scc1 .Lnsa_fast_A
	ds_read_b128 v[244:247], v238 offset:16384
	ds_read_b128 v[248:251], v238 offset:20992
	v_and_b32_e32 v32, s15, v234
	v_cmp_ne_u32_e32 vcc, 0, v32
	s_cmp_lg_u32 s10, s89
	s_cselect_b64 s[78:79], -1, 0
	v_cndmask_b32_e64 v32, v208, -v232, vcc
	v_mov_b32_e32 v33, v32
	v_mov_b32_e32 v34, v32
	v_mov_b32_e32 v35, v32
	v_mov_b32_e32 v36, v32
	v_mov_b32_e32 v37, v32
	v_mov_b32_e32 v38, v32
	v_mov_b32_e32 v39, v32
	v_mov_b32_e32 v40, v32
	v_mov_b32_e32 v41, v32
	v_mov_b32_e32 v42, v32
	v_mov_b32_e32 v43, v32
	v_mov_b32_e32 v44, v32
	v_mov_b32_e32 v45, v32
	v_mov_b32_e32 v46, v32
	v_mov_b32_e32 v47, v32
	s_cmp_lg_u32 s10, s8
	s_cselect_b64 vcc, -1, 0
	s_waitcnt lgkmcnt(1)
	v_mfma_f32_32x32x16_bf16 v[48:63], v[244:247], v[64:67], v[32:47]
	ds_read_b128 v[244:247], v238 offset:16416
	s_and_b64 s[78:79], s[78:79], vcc
	s_and_b64 vcc, exec, s[78:79]
	s_waitcnt lgkmcnt(1)
	v_mfma_f32_32x32x16_bf16 v[32:47], v[248:251], v[64:67], v[32:47]
	ds_read_b128 v[248:251], v238 offset:21024
	s_waitcnt lgkmcnt(1)
	v_mfma_f32_32x32x16_bf16 v[48:63], v[244:247], v[68:71], v[48:63]
	ds_read_b128 v[244:247], v238 offset:16448
	s_waitcnt lgkmcnt(1)
	v_mfma_f32_32x32x16_bf16 v[32:47], v[248:251], v[68:71], v[32:47]
	ds_read_b128 v[248:251], v238 offset:21056
	s_waitcnt lgkmcnt(1)
	v_mfma_f32_32x32x16_bf16 v[48:63], v[244:247], v[72:75], v[48:63]
	ds_read_b128 v[244:247], v238 offset:16480
	s_waitcnt lgkmcnt(1)
	v_mfma_f32_32x32x16_bf16 v[32:47], v[248:251], v[72:75], v[32:47]
	ds_read_b128 v[248:251], v238 offset:21088
	s_waitcnt lgkmcnt(1)
	v_mfma_f32_32x32x16_bf16 v[48:63], v[244:247], v[76:79], v[48:63]
	s_waitcnt lgkmcnt(0)
	v_mfma_f32_32x32x16_bf16 v[32:47], v[248:251], v[76:79], v[32:47]
	s_cbranch_vccnz .LBB0_126
	v_lshl_or_b32 v156, s10, 6, v102
	v_cmp_lt_i32_e32 vcc, v156, v233
	v_cmp_gt_i32_e64 s[78:79], v156, v117
	s_or_b64 vcc, vcc, s[78:79]
	v_or_b32_e32 v157, 32, v156
	s_nop 2
	v_cndmask_b32_e32 v48, v48, v208, vcc
	v_cmp_lt_i32_e32 vcc, v157, v233
	v_cmp_gt_i32_e64 s[78:79], v157, v117
	s_or_b64 vcc, vcc, s[78:79]
	v_or_b32_e32 v157, 1, v156
	v_cndmask_b32_e32 v32, v32, v208, vcc
	v_cmp_lt_i32_e32 vcc, v157, v233
	v_cmp_ge_i32_e64 s[78:79], v156, v117
	s_or_b64 vcc, s[78:79], vcc
	v_or_b32_e32 v157, 33, v156
	v_cndmask_b32_e32 v49, v49, v208, vcc
	v_cmp_lt_i32_e32 vcc, v157, v233
	v_cmp_gt_i32_e64 s[78:79], v157, v117
	s_or_b64 vcc, vcc, s[78:79]
	v_or_b32_e32 v157, 2, v156
	v_cndmask_b32_e32 v33, v33, v208, vcc
	v_cmp_lt_i32_e32 vcc, v157, v233
	v_cmp_gt_i32_e64 s[78:79], v157, v117
	s_or_b64 vcc, vcc, s[78:79]
	v_or_b32_e32 v157, 34, v156
	v_cndmask_b32_e32 v50, v50, v208, vcc
	v_cmp_lt_i32_e32 vcc, v157, v233
	v_cmp_gt_i32_e64 s[78:79], v157, v117
	s_or_b64 vcc, vcc, s[78:79]
	v_or_b32_e32 v157, 3, v156
	v_cndmask_b32_e32 v34, v34, v208, vcc
	v_cmp_lt_i32_e32 vcc, v157, v233
	v_cmp_gt_i32_e64 s[78:79], v157, v117
	s_or_b64 vcc, vcc, s[78:79]
	v_or_b32_e32 v157, 35, v156
	v_cndmask_b32_e32 v51, v51, v208, vcc
	v_cmp_lt_i32_e32 vcc, v157, v233
	v_cmp_gt_i32_e64 s[78:79], v157, v117
	s_or_b64 vcc, vcc, s[78:79]
	v_or_b32_e32 v157, 8, v156
	v_cndmask_b32_e32 v35, v35, v208, vcc
	v_cmp_lt_i32_e32 vcc, v157, v233
	v_cmp_gt_i32_e64 s[78:79], v157, v117
	s_or_b64 vcc, vcc, s[78:79]
	v_or_b32_e32 v157, 40, v156
	v_cndmask_b32_e32 v52, v52, v208, vcc
	v_cmp_lt_i32_e32 vcc, v157, v233
	v_cmp_gt_i32_e64 s[78:79], v157, v117
	s_or_b64 vcc, vcc, s[78:79]
	v_or_b32_e32 v157, 9, v156
	v_cndmask_b32_e32 v36, v36, v208, vcc
	v_cmp_lt_i32_e32 vcc, v157, v233
	v_cmp_gt_i32_e64 s[78:79], v157, v117
	s_or_b64 vcc, vcc, s[78:79]
	v_or_b32_e32 v157, 41, v156
	v_cndmask_b32_e32 v53, v53, v208, vcc
	v_cmp_lt_i32_e32 vcc, v157, v233
	v_cmp_gt_i32_e64 s[78:79], v157, v117
	s_or_b64 vcc, vcc, s[78:79]
	v_or_b32_e32 v157, 10, v156
	v_cndmask_b32_e32 v37, v37, v208, vcc
	v_cmp_lt_i32_e32 vcc, v157, v233
	v_cmp_gt_i32_e64 s[78:79], v157, v117
	s_or_b64 vcc, vcc, s[78:79]
	v_or_b32_e32 v157, 42, v156
	v_cndmask_b32_e32 v54, v54, v208, vcc
	v_cmp_lt_i32_e32 vcc, v157, v233
	v_cmp_gt_i32_e64 s[78:79], v157, v117
	s_or_b64 vcc, vcc, s[78:79]
	v_or_b32_e32 v157, 11, v156
	v_cndmask_b32_e32 v38, v38, v208, vcc
	v_cmp_lt_i32_e32 vcc, v157, v233
	v_cmp_gt_i32_e64 s[78:79], v157, v117
	s_or_b64 vcc, vcc, s[78:79]
	v_or_b32_e32 v157, 43, v156
	v_cndmask_b32_e32 v55, v55, v208, vcc
	v_cmp_lt_i32_e32 vcc, v157, v233
	v_cmp_gt_i32_e64 s[78:79], v157, v117
	s_or_b64 vcc, vcc, s[78:79]
	v_or_b32_e32 v157, 16, v156
	v_cndmask_b32_e32 v39, v39, v208, vcc
	v_cmp_lt_i32_e32 vcc, v157, v233
	v_cmp_gt_i32_e64 s[78:79], v157, v117
	s_or_b64 vcc, vcc, s[78:79]
	v_or_b32_e32 v157, 48, v156
	v_cndmask_b32_e32 v56, v56, v208, vcc
	v_cmp_lt_i32_e32 vcc, v157, v233
	v_cmp_gt_i32_e64 s[78:79], v157, v117
	s_or_b64 vcc, vcc, s[78:79]
	v_or_b32_e32 v157, 17, v156
	v_cndmask_b32_e32 v40, v40, v208, vcc
	v_cmp_lt_i32_e32 vcc, v157, v233
	v_cmp_gt_i32_e64 s[78:79], v157, v117
	s_or_b64 vcc, vcc, s[78:79]
	v_or_b32_e32 v157, 49, v156
	v_cndmask_b32_e32 v57, v57, v208, vcc
	v_cmp_lt_i32_e32 vcc, v157, v233
	v_cmp_gt_i32_e64 s[78:79], v157, v117
	s_or_b64 vcc, vcc, s[78:79]
	v_or_b32_e32 v157, 18, v156
	v_cndmask_b32_e32 v41, v41, v208, vcc
	v_cmp_lt_i32_e32 vcc, v157, v233
	v_cmp_gt_i32_e64 s[78:79], v157, v117
	s_or_b64 vcc, vcc, s[78:79]
	v_or_b32_e32 v157, 50, v156
	v_cndmask_b32_e32 v58, v58, v208, vcc
	v_cmp_lt_i32_e32 vcc, v157, v233
	v_cmp_gt_i32_e64 s[78:79], v157, v117
	s_or_b64 vcc, vcc, s[78:79]
	v_or_b32_e32 v157, 19, v156
	v_cndmask_b32_e32 v42, v42, v208, vcc
	v_cmp_lt_i32_e32 vcc, v157, v233
	v_cmp_gt_i32_e64 s[78:79], v157, v117
	s_or_b64 vcc, vcc, s[78:79]
	v_or_b32_e32 v157, 51, v156
	v_cndmask_b32_e32 v59, v59, v208, vcc
	v_cmp_lt_i32_e32 vcc, v157, v233
	v_cmp_gt_i32_e64 s[78:79], v157, v117
	s_or_b64 vcc, vcc, s[78:79]
	v_or_b32_e32 v157, 24, v156
	v_cndmask_b32_e32 v43, v43, v208, vcc
	v_cmp_lt_i32_e32 vcc, v157, v233
	v_cmp_gt_i32_e64 s[78:79], v157, v117
	s_or_b64 vcc, vcc, s[78:79]
	v_or_b32_e32 v157, 56, v156
	v_cndmask_b32_e32 v60, v60, v208, vcc
	v_cmp_lt_i32_e32 vcc, v157, v233
	v_cmp_gt_i32_e64 s[78:79], v157, v117
	s_or_b64 vcc, vcc, s[78:79]
	v_or_b32_e32 v157, 25, v156
	v_cndmask_b32_e32 v44, v44, v208, vcc
	v_cmp_lt_i32_e32 vcc, v157, v233
	v_cmp_gt_i32_e64 s[78:79], v157, v117
	s_or_b64 vcc, vcc, s[78:79]
	v_or_b32_e32 v157, 57, v156
	v_cndmask_b32_e32 v61, v61, v208, vcc
	v_cmp_lt_i32_e32 vcc, v157, v233
	v_cmp_gt_i32_e64 s[78:79], v157, v117
	s_or_b64 vcc, vcc, s[78:79]
	v_or_b32_e32 v157, 26, v156
	v_cndmask_b32_e32 v45, v45, v208, vcc
	v_cmp_lt_i32_e32 vcc, v157, v233
	v_cmp_gt_i32_e64 s[78:79], v157, v117
	s_or_b64 vcc, vcc, s[78:79]
	v_or_b32_e32 v157, 58, v156
	v_cndmask_b32_e32 v62, v62, v208, vcc
	v_cmp_lt_i32_e32 vcc, v157, v233
	v_cmp_gt_i32_e64 s[78:79], v157, v117
	s_or_b64 vcc, vcc, s[78:79]
	v_or_b32_e32 v157, 27, v156
	v_cndmask_b32_e32 v46, v46, v208, vcc
	v_cmp_lt_i32_e32 vcc, v157, v233
	v_cmp_gt_i32_e64 s[78:79], v157, v117
	s_or_b64 vcc, vcc, s[78:79]
	v_or_b32_e32 v156, 59, v156
	v_cndmask_b32_e32 v63, v63, v208, vcc
	v_cmp_lt_i32_e32 vcc, v156, v233
	v_cmp_gt_i32_e64 s[78:79], v156, v117
	s_or_b64 vcc, vcc, s[78:79]
	v_cndmask_b32_e32 v47, v47, v208, vcc
.LBB0_126:
	s_nop 7
	v_exp_f32_e32 v210, v48
	s_nop 1
	v_exp_f32_e32 v211, v32
	v_exp_f32_e32 v160, v49
	v_exp_f32_e32 v156, v33
	v_exp_f32_e32 v196, v34
	v_add_f32_e32 v157, v211, v210
	v_exp_f32_e32 v48, v35
	v_pk_add_f32 v[32:33], v[156:157], v[160:161]
	v_exp_f32_e32 v157, v50
	v_pk_add_f32 v[244:245], v[32:33], v[32:33] op_sel_hi:[0,1]
	v_exp_f32_e32 v244, v51
	v_exp_f32_e32 v50, v37
	v_add_f32_e32 v49, v196, v157
	v_pk_add_f32 v[32:33], v[48:49], v[244:245]
	s_nop 0
	v_pk_add_f32 v[246:247], v[32:33], v[32:33] op_sel_hi:[0,1]
	v_exp_f32_e32 v49, v52
	v_exp_f32_e32 v245, v36
	v_exp_f32_e32 v246, v53
	v_exp_f32_e32 v52, v39
	v_add_f32_e32 v51, v245, v49
	v_pk_add_f32 v[32:33], v[50:51], v[246:247]
	v_exp_f32_e32 v51, v54
	v_pk_add_f32 v[248:249], v[32:33], v[32:33] op_sel_hi:[0,1]
	v_exp_f32_e32 v247, v38
	v_exp_f32_e32 v248, v55
	v_add_f32_e32 v53, v247, v51
	v_pk_add_f32 v[32:33], v[52:53], v[248:249]
	v_exp_f32_e32 v53, v56
	v_pk_add_f32 v[54:55], v[32:33], v[32:33] op_sel_hi:[0,1]
	v_exp_f32_e32 v249, v40
	v_exp_f32_e32 v54, v57
	v_exp_f32_e32 v32, v41
	v_add_f32_e32 v33, v249, v53
	v_pk_add_f32 v[34:35], v[32:33], v[54:55]
	s_nop 0
	v_pk_add_f32 v[250:251], v[34:35], v[34:35] op_sel_hi:[0,1]
	v_exp_f32_e32 v33, v58
	v_exp_f32_e32 v55, v42
	v_exp_f32_e32 v250, v59
	v_exp_f32_e32 v34, v43
	v_cvt_pk_bf16_f32 v42, v49, v246
	v_add_f32_e32 v35, v55, v33
	v_cvt_pk_bf16_f32 v43, v51, v248
	v_pk_add_f32 v[36:37], v[34:35], v[250:251]
	v_exp_f32_e32 v35, v60
	v_pk_add_f32 v[206:207], v[36:37], v[36:37] op_sel_hi:[0,1]
	v_exp_f32_e32 v251, v44
	v_exp_f32_e32 v206, v61
	v_exp_f32_e32 v36, v45
	v_add_u32_e32 v49, 0x7000, v239
	v_add_f32_e32 v37, v251, v35
	v_cvt_pk_bf16_f32 v32, v249, v32
	v_pk_add_f32 v[38:39], v[36:37], v[206:207]
	v_exp_f32_e32 v37, v62
	v_pk_add_f32 v[60:61], v[38:39], v[38:39] op_sel_hi:[0,1]
	v_exp_f32_e32 v62, v46
	v_exp_f32_e32 v60, v63
	v_exp_f32_e32 v38, v47
	v_add_f32_e32 v39, v62, v37
	v_pk_add_f32 v[40:41], v[38:39], v[60:61]
	s_nop 0
	v_add_f32_e32 v39, v40, v41
	v_add_f32_e32 v115, v115, v39
	v_add_u32_e32 v39, 0x6000, v239
	ds_read2_b64 v[44:47], v39 offset0:128 offset1:130
	ds_read2_b64 v[56:59], v39 offset0:132 offset1:134
	v_cvt_pk_bf16_f32 v40, v210, v160
	v_cvt_pk_bf16_f32 v41, v157, v244
	s_waitcnt lgkmcnt(1)
	s_nop 0
	v_mfma_f32_32x32x16_bf16 v[0:15], v[44:47], v[40:43], v[0:15]
	ds_read2_b64 v[44:47], v49 offset0:160 offset1:162
	s_waitcnt lgkmcnt(0)
	v_mfma_f32_32x32x16_bf16 v[16:31], v[44:47], v[40:43], v[16:31]
	ds_read2_b64 v[44:47], v49 offset0:164 offset1:166
	v_cvt_pk_bf16_f32 v40, v53, v54
	v_cvt_pk_bf16_f32 v41, v33, v250
	v_cvt_pk_bf16_f32 v42, v35, v206
	v_cvt_pk_bf16_f32 v43, v37, v60
	v_cvt_pk_bf16_f32 v33, v55, v34
	v_cvt_pk_bf16_f32 v34, v251, v36
	s_waitcnt lgkmcnt(0)
	v_mfma_f32_32x32x16_bf16 v[16:31], v[44:47], v[40:43], v[16:31]
	ds_read2_b64 v[44:47], v39 offset0:136 offset1:138
	v_cvt_pk_bf16_f32 v35, v62, v38
	ds_read2_b64 v[36:39], v39 offset0:140 offset1:142
	v_mfma_f32_32x32x16_bf16 v[0:15], v[56:59], v[40:43], v[0:15]
	v_cvt_pk_bf16_f32 v40, v211, v156
	v_cvt_pk_bf16_f32 v41, v196, v48
	v_cvt_pk_bf16_f32 v42, v245, v50
	v_cvt_pk_bf16_f32 v43, v247, v52
	s_waitcnt lgkmcnt(1)
	s_nop 0
	v_mfma_f32_32x32x16_bf16 v[0:15], v[44:47], v[40:43], v[0:15]
	ds_read2_b64 v[44:47], v49 offset0:168 offset1:170
	s_waitcnt lgkmcnt(1)
	v_mfma_f32_32x32x16_bf16 v[0:15], v[36:39], v[32:35], v[0:15]
	ds_read2_b64 v[36:39], v49 offset0:172 offset1:174
	s_waitcnt lgkmcnt(1)
	v_mfma_f32_32x32x16_bf16 v[16:31], v[44:47], v[40:43], v[16:31]
	s_waitcnt lgkmcnt(0)
	v_mfma_f32_32x32x16_bf16 v[16:31], v[36:39], v[32:35], v[16:31]
	s_branch .LBB0_127
.Lnsa_fast_A:
	ds_read_b128 v[244:247], v238 offset:16384
	ds_read_b128 v[248:251], v238 offset:16416
	v_and_b32_e32 v32, s15, v234
	v_cmp_ne_u32_e32 vcc, 0, v32
	v_add_u32_e32 v210, 0x6000, v239
	v_add_u32_e32 v211, 0x7000, v239
	v_cndmask_b32_e64 v32, v208, -v232, vcc
	v_mov_b32_e32 v33, v32
	v_mov_b32_e32 v34, v32
	v_mov_b32_e32 v35, v32
	v_mov_b32_e32 v36, v32
	v_mov_b32_e32 v37, v32
	v_mov_b32_e32 v38, v32
	v_mov_b32_e32 v39, v32
	v_mov_b32_e32 v40, v32
	v_mov_b32_e32 v41, v32
	v_mov_b32_e32 v42, v32
	v_mov_b32_e32 v43, v32
	v_mov_b32_e32 v44, v32
	v_mov_b32_e32 v45, v32
	v_mov_b32_e32 v46, v32
	v_mov_b32_e32 v47, v32
	s_waitcnt lgkmcnt(1)
	v_mfma_f32_32x32x16_bf16 v[48:63], v[244:247], v[64:67], v[32:47]
	ds_read_b128 v[244:247], v238 offset:16448
	s_waitcnt lgkmcnt(1)
	v_mfma_f32_32x32x16_bf16 v[48:63], v[248:251], v[68:71], v[48:63]
	ds_read_b128 v[248:251], v238 offset:16480
	s_waitcnt lgkmcnt(1)
	v_mfma_f32_32x32x16_bf16 v[48:63], v[244:247], v[72:75], v[48:63]
	ds_read_b128 v[244:247], v238 offset:20992
	s_waitcnt lgkmcnt(1)
	v_mfma_f32_32x32x16_bf16 v[48:63], v[248:251], v[76:79], v[48:63]
	ds_read_b128 v[248:251], v238 offset:21024
	s_waitcnt lgkmcnt(1)
	v_mfma_f32_32x32x16_bf16 v[32:47], v[244:247], v[64:67], v[32:47]
	ds_read_b128 v[244:247], v238 offset:21056
	s_nop 7
	s_nop 7
	v_exp_f32_e32 v48, v48
	v_exp_f32_e32 v49, v49
	v_exp_f32_e32 v50, v50
	v_exp_f32_e32 v51, v51
	s_waitcnt lgkmcnt(1)
	v_mfma_f32_32x32x16_bf16 v[32:47], v[248:251], v[68:71], v[32:47]
	ds_read_b128 v[248:251], v238 offset:21088
	v_exp_f32_e32 v52, v52
	v_exp_f32_e32 v53, v53
	v_exp_f32_e32 v54, v54
	v_exp_f32_e32 v55, v55
	v_add_f32_e32 v156, v48, v49
	v_add_f32_e32 v157, v50, v51
	s_waitcnt lgkmcnt(1)
	v_mfma_f32_32x32x16_bf16 v[32:47], v[244:247], v[72:75], v[32:47]
	v_exp_f32_e32 v56, v56
	v_exp_f32_e32 v57, v57
	v_exp_f32_e32 v58, v58
	v_exp_f32_e32 v59, v59
	v_add_f32_e32 v160, v52, v53
	v_add_f32_e32 v196, v54, v55
	s_waitcnt lgkmcnt(0)
	v_mfma_f32_32x32x16_bf16 v[32:47], v[248:251], v[76:79], v[32:47]
	ds_read2_b64 v[244:247], v210 offset0:132 offset1:134
	ds_read2_b64 v[248:251], v211 offset0:164 offset1:166
	v_exp_f32_e32 v60, v60
	v_exp_f32_e32 v61, v61
	v_exp_f32_e32 v62, v62
	v_exp_f32_e32 v63, v63
	v_add_f32_e32 v156, v156, v157
	v_add_f32_e32 v160, v160, v196
	v_add_f32_e32 v157, v56, v57
	v_add_f32_e32 v196, v58, v59
	v_add_f32_e32 v156, v156, v160
	v_add_f32_e32 v157, v157, v196
	v_add_f32_e32 v160, v60, v61
	v_add_f32_e32 v196, v62, v63
	v_add_f32_e32 v160, v160, v196
	v_add_f32_e32 v157, v157, v160
	v_add_f32_e32 v156, v156, v157
	v_add_f32_e32 v115, v115, v156
	v_cvt_pk_bf16_f32 v48, v48, v49
	v_cvt_pk_bf16_f32 v49, v50, v51
	v_cvt_pk_bf16_f32 v50, v52, v53
	v_cvt_pk_bf16_f32 v51, v54, v55
	v_cvt_pk_bf16_f32 v52, v56, v57
	v_cvt_pk_bf16_f32 v53, v58, v59
	v_cvt_pk_bf16_f32 v54, v60, v61
	v_cvt_pk_bf16_f32 v55, v62, v63
	ds_read2_b64 v[56:59], v210 offset0:128 offset1:130
	ds_read2_b64 v[60:63], v211 offset0:160 offset1:162
	s_waitcnt lgkmcnt(3)
	v_mfma_f32_32x32x16_bf16 v[0:15], v[244:247], v[52:55], v[0:15]
	ds_read2_b64 v[244:247], v210 offset0:136 offset1:138
	v_exp_f32_e32 v32, v32
	v_exp_f32_e32 v33, v33
	v_exp_f32_e32 v34, v34
	v_exp_f32_e32 v35, v35
	s_waitcnt lgkmcnt(3)
	v_mfma_f32_32x32x16_bf16 v[16:31], v[248:251], v[52:55], v[16:31]
	ds_read2_b64 v[248:251], v211 offset0:168 offset1:170
	v_exp_f32_e32 v36, v36
	v_exp_f32_e32 v37, v37
	v_exp_f32_e32 v38, v38
	v_exp_f32_e32 v39, v39
	v_add_f32_e32 v156, v32, v33
	v_add_f32_e32 v157, v34, v35
	s_waitcnt lgkmcnt(3)
	v_mfma_f32_32x32x16_bf16 v[0:15], v[56:59], v[48:51], v[0:15]
	ds_read2_b64 v[56:59], v210 offset0:140 offset1:142
	v_exp_f32_e32 v40, v40
	v_exp_f32_e32 v41, v41
	v_exp_f32_e32 v42, v42
	v_exp_f32_e32 v43, v43
	v_add_f32_e32 v160, v36, v37
	v_add_f32_e32 v196, v38, v39
	s_waitcnt lgkmcnt(3)
	v_mfma_f32_32x32x16_bf16 v[16:31], v[60:63], v[48:51], v[16:31]
	ds_read2_b64 v[60:63], v211 offset0:172 offset1:174
	v_exp_f32_e32 v44, v44
	v_exp_f32_e32 v45, v45
	v_exp_f32_e32 v46, v46
	v_exp_f32_e32 v47, v47
	v_add_f32_e32 v156, v156, v157
	v_add_f32_e32 v160, v160, v196
	v_add_f32_e32 v157, v40, v41
	v_add_f32_e32 v196, v42, v43
	v_add_f32_e32 v156, v156, v160
	v_add_f32_e32 v157, v157, v196
	v_add_f32_e32 v160, v44, v45
	v_add_f32_e32 v196, v46, v47
	v_add_f32_e32 v160, v160, v196
	v_add_f32_e32 v157, v157, v160
	v_add_f32_e32 v156, v156, v157
	v_add_f32_e32 v115, v115, v156
	v_cvt_pk_bf16_f32 v32, v32, v33
	v_cvt_pk_bf16_f32 v33, v34, v35
	v_cvt_pk_bf16_f32 v34, v36, v37
	v_cvt_pk_bf16_f32 v35, v38, v39
	v_cvt_pk_bf16_f32 v36, v40, v41
	v_cvt_pk_bf16_f32 v37, v42, v43
	v_cvt_pk_bf16_f32 v38, v44, v45
	v_cvt_pk_bf16_f32 v39, v46, v47
	s_waitcnt lgkmcnt(3)
	s_nop 0
	v_mfma_f32_32x32x16_bf16 v[0:15], v[244:247], v[32:35], v[0:15]
	s_waitcnt lgkmcnt(2)
	v_mfma_f32_32x32x16_bf16 v[16:31], v[248:251], v[32:35], v[16:31]
	s_waitcnt lgkmcnt(1)
	v_mfma_f32_32x32x16_bf16 v[0:15], v[56:59], v[36:39], v[0:15]
	s_waitcnt lgkmcnt(0)
	v_mfma_f32_32x32x16_bf16 v[16:31], v[60:63], v[36:39], v[16:31]
.LBB0_127:
	s_or_b64 exec, exec, s[84:85]
	s_cmp_lt_i32 s11, 0
	s_cbranch_scc1 .LBB0_131
	s_and_b32 s12, s13, s12
	v_sub_co_u32_e64 v36, s[78:79], s12, 1
	s_ff1_i32_b32 s10, s12
	s_and_b64 s[78:79], s[78:79], exec
	s_cselect_b32 s13, -1, s10
	s_max_i32 s10, s13, 0
	v_lshl_add_u32 v32, s10, 6, v231
	v_ashrrev_i32_e32 v33, 31, v32
	s_waitcnt vmcnt(2)
	ds_write_b128 v240, v[88:91] offset:16384
	ds_write2_b64 v241, v[92:93], v[94:95] offset1:1
	v_lshlrev_b64 v[32:33], 11, v[32:33]
	s_waitcnt lgkmcnt(0)
	s_barrier
	v_lshl_add_u64 v[32:33], v[152:153], 0, v[32:33]
	s_lshl_b32 s92, s10, 13
	v_lshl_add_u64 v[34:35], v[154:155], 0, s[92:93]
	global_load_dwordx4 v[88:91], v[32:33], off
	global_load_dwordx4 v[92:95], v[34:35], off
	s_lshl_b32 s10, 1, s11
	v_and_b32_e32 v32, s10, v235
	v_readfirstlane_b32 s92, v36
	v_cmp_ne_u32_e32 vcc, 0, v32
	s_and_saveexec_b64 s[84:85], vcc
	s_cbranch_execz .LBB0_122
	s_cmp_lg_u32 s11, s89
	s_cselect_b64 s[98:99], -1, 0
	s_cmp_lg_u32 s11, s8
	s_cselect_b64 vcc, -1, 0
	s_and_b64 s[98:99], s[98:99], vcc
	s_cbranch_scc1 .Lnsa_fast_B
	ds_read_b128 v[244:247], v242 offset:16384
	ds_read_b128 v[248:251], v242 offset:20992
	v_and_b32_e32 v32, s10, v234
	v_cmp_ne_u32_e32 vcc, 0, v32
	s_cmp_lg_u32 s11, s89
	s_cselect_b64 s[78:79], -1, 0
	v_cndmask_b32_e64 v32, v208, -v232, vcc
	v_mov_b32_e32 v33, v32
	v_mov_b32_e32 v34, v32
	v_mov_b32_e32 v35, v32
	v_mov_b32_e32 v36, v32
	v_mov_b32_e32 v37, v32
	v_mov_b32_e32 v38, v32
	v_mov_b32_e32 v39, v32
	v_mov_b32_e32 v40, v32
	v_mov_b32_e32 v41, v32
	v_mov_b32_e32 v42, v32
	v_mov_b32_e32 v43, v32
	v_mov_b32_e32 v44, v32
	v_mov_b32_e32 v45, v32
	v_mov_b32_e32 v46, v32
	v_mov_b32_e32 v47, v32
	s_cmp_lg_u32 s11, s8
	s_cselect_b64 vcc, -1, 0
	s_waitcnt lgkmcnt(1)
	v_mfma_f32_32x32x16_bf16 v[48:63], v[244:247], v[64:67], v[32:47]
	ds_read_b128 v[244:247], v242 offset:16416
	s_and_b64 s[78:79], s[78:79], vcc
	s_and_b64 vcc, exec, s[78:79]
	s_waitcnt lgkmcnt(1)
	v_mfma_f32_32x32x16_bf16 v[32:47], v[248:251], v[64:67], v[32:47]
	ds_read_b128 v[248:251], v242 offset:21024
	s_waitcnt lgkmcnt(1)
	v_mfma_f32_32x32x16_bf16 v[48:63], v[244:247], v[68:71], v[48:63]
	ds_read_b128 v[244:247], v242 offset:16448
	s_waitcnt lgkmcnt(1)
	v_mfma_f32_32x32x16_bf16 v[32:47], v[248:251], v[68:71], v[32:47]
	ds_read_b128 v[248:251], v242 offset:21056
	s_waitcnt lgkmcnt(1)
	v_mfma_f32_32x32x16_bf16 v[48:63], v[244:247], v[72:75], v[48:63]
	ds_read_b128 v[244:247], v242 offset:16480
	s_waitcnt lgkmcnt(1)
	v_mfma_f32_32x32x16_bf16 v[32:47], v[248:251], v[72:75], v[32:47]
	ds_read_b128 v[248:251], v242 offset:21088
	s_waitcnt lgkmcnt(1)
	v_mfma_f32_32x32x16_bf16 v[48:63], v[244:247], v[76:79], v[48:63]
	s_waitcnt lgkmcnt(0)
	v_mfma_f32_32x32x16_bf16 v[32:47], v[248:251], v[76:79], v[32:47]
	s_cbranch_vccnz .LBB0_121
	v_lshl_or_b32 v156, s11, 6, v102
	v_cmp_lt_i32_e32 vcc, v156, v233
	v_cmp_gt_i32_e64 s[78:79], v156, v117
	s_or_b64 vcc, vcc, s[78:79]
	v_or_b32_e32 v157, 32, v156
	s_nop 2
	v_cndmask_b32_e32 v48, v48, v208, vcc
	v_cmp_lt_i32_e32 vcc, v157, v233
	v_cmp_gt_i32_e64 s[78:79], v157, v117
	s_or_b64 vcc, vcc, s[78:79]
	v_or_b32_e32 v157, 1, v156
	v_cndmask_b32_e32 v32, v32, v208, vcc
	v_cmp_lt_i32_e32 vcc, v157, v233
	v_cmp_ge_i32_e64 s[78:79], v156, v117
	s_or_b64 vcc, s[78:79], vcc
	v_or_b32_e32 v157, 33, v156
	v_cndmask_b32_e32 v49, v49, v208, vcc
	v_cmp_lt_i32_e32 vcc, v157, v233
	v_cmp_gt_i32_e64 s[78:79], v157, v117
	s_or_b64 vcc, vcc, s[78:79]
	v_or_b32_e32 v157, 2, v156
	v_cndmask_b32_e32 v33, v33, v208, vcc
	v_cmp_lt_i32_e32 vcc, v157, v233
	v_cmp_gt_i32_e64 s[78:79], v157, v117
	s_or_b64 vcc, vcc, s[78:79]
	v_or_b32_e32 v157, 34, v156
	v_cndmask_b32_e32 v50, v50, v208, vcc
	v_cmp_lt_i32_e32 vcc, v157, v233
	v_cmp_gt_i32_e64 s[78:79], v157, v117
	s_or_b64 vcc, vcc, s[78:79]
	v_or_b32_e32 v157, 3, v156
	v_cndmask_b32_e32 v34, v34, v208, vcc
	v_cmp_lt_i32_e32 vcc, v157, v233
	v_cmp_gt_i32_e64 s[78:79], v157, v117
	s_or_b64 vcc, vcc, s[78:79]
	v_or_b32_e32 v157, 35, v156
	v_cndmask_b32_e32 v51, v51, v208, vcc
	v_cmp_lt_i32_e32 vcc, v157, v233
	v_cmp_gt_i32_e64 s[78:79], v157, v117
	s_or_b64 vcc, vcc, s[78:79]
	v_or_b32_e32 v157, 8, v156
	v_cndmask_b32_e32 v35, v35, v208, vcc
	v_cmp_lt_i32_e32 vcc, v157, v233
	v_cmp_gt_i32_e64 s[78:79], v157, v117
	s_or_b64 vcc, vcc, s[78:79]
	v_or_b32_e32 v157, 40, v156
	v_cndmask_b32_e32 v52, v52, v208, vcc
	v_cmp_lt_i32_e32 vcc, v157, v233
	v_cmp_gt_i32_e64 s[78:79], v157, v117
	s_or_b64 vcc, vcc, s[78:79]
	v_or_b32_e32 v157, 9, v156
	v_cndmask_b32_e32 v36, v36, v208, vcc
	v_cmp_lt_i32_e32 vcc, v157, v233
	v_cmp_gt_i32_e64 s[78:79], v157, v117
	s_or_b64 vcc, vcc, s[78:79]
	v_or_b32_e32 v157, 41, v156
	v_cndmask_b32_e32 v53, v53, v208, vcc
	v_cmp_lt_i32_e32 vcc, v157, v233
	v_cmp_gt_i32_e64 s[78:79], v157, v117
	s_or_b64 vcc, vcc, s[78:79]
	v_or_b32_e32 v157, 10, v156
	v_cndmask_b32_e32 v37, v37, v208, vcc
	v_cmp_lt_i32_e32 vcc, v157, v233
	v_cmp_gt_i32_e64 s[78:79], v157, v117
	s_or_b64 vcc, vcc, s[78:79]
	v_or_b32_e32 v157, 42, v156
	v_cndmask_b32_e32 v54, v54, v208, vcc
	v_cmp_lt_i32_e32 vcc, v157, v233
	v_cmp_gt_i32_e64 s[78:79], v157, v117
	s_or_b64 vcc, vcc, s[78:79]
	v_or_b32_e32 v157, 11, v156
	v_cndmask_b32_e32 v38, v38, v208, vcc
	v_cmp_lt_i32_e32 vcc, v157, v233
	v_cmp_gt_i32_e64 s[78:79], v157, v117
	s_or_b64 vcc, vcc, s[78:79]
	v_or_b32_e32 v157, 43, v156
	v_cndmask_b32_e32 v55, v55, v208, vcc
	v_cmp_lt_i32_e32 vcc, v157, v233
	v_cmp_gt_i32_e64 s[78:79], v157, v117
	s_or_b64 vcc, vcc, s[78:79]
	v_or_b32_e32 v157, 16, v156
	v_cndmask_b32_e32 v39, v39, v208, vcc
	v_cmp_lt_i32_e32 vcc, v157, v233
	v_cmp_gt_i32_e64 s[78:79], v157, v117
	s_or_b64 vcc, vcc, s[78:79]
	v_or_b32_e32 v157, 48, v156
	v_cndmask_b32_e32 v56, v56, v208, vcc
	v_cmp_lt_i32_e32 vcc, v157, v233
	v_cmp_gt_i32_e64 s[78:79], v157, v117
	s_or_b64 vcc, vcc, s[78:79]
	v_or_b32_e32 v157, 17, v156
	v_cndmask_b32_e32 v40, v40, v208, vcc
	v_cmp_lt_i32_e32 vcc, v157, v233
	v_cmp_gt_i32_e64 s[78:79], v157, v117
	s_or_b64 vcc, vcc, s[78:79]
	v_or_b32_e32 v157, 49, v156
	v_cndmask_b32_e32 v57, v57, v208, vcc
	v_cmp_lt_i32_e32 vcc, v157, v233
	v_cmp_gt_i32_e64 s[78:79], v157, v117
	s_or_b64 vcc, vcc, s[78:79]
	v_or_b32_e32 v157, 18, v156
	v_cndmask_b32_e32 v41, v41, v208, vcc
	v_cmp_lt_i32_e32 vcc, v157, v233
	v_cmp_gt_i32_e64 s[78:79], v157, v117
	s_or_b64 vcc, vcc, s[78:79]
	v_or_b32_e32 v157, 50, v156
	v_cndmask_b32_e32 v58, v58, v208, vcc
	v_cmp_lt_i32_e32 vcc, v157, v233
	v_cmp_gt_i32_e64 s[78:79], v157, v117
	s_or_b64 vcc, vcc, s[78:79]
	v_or_b32_e32 v157, 19, v156
	v_cndmask_b32_e32 v42, v42, v208, vcc
	v_cmp_lt_i32_e32 vcc, v157, v233
	v_cmp_gt_i32_e64 s[78:79], v157, v117
	s_or_b64 vcc, vcc, s[78:79]
	v_or_b32_e32 v157, 51, v156
	v_cndmask_b32_e32 v59, v59, v208, vcc
	v_cmp_lt_i32_e32 vcc, v157, v233
	v_cmp_gt_i32_e64 s[78:79], v157, v117
	s_or_b64 vcc, vcc, s[78:79]
	v_or_b32_e32 v157, 24, v156
	v_cndmask_b32_e32 v43, v43, v208, vcc
	v_cmp_lt_i32_e32 vcc, v157, v233
	v_cmp_gt_i32_e64 s[78:79], v157, v117
	s_or_b64 vcc, vcc, s[78:79]
	v_or_b32_e32 v157, 56, v156
	v_cndmask_b32_e32 v60, v60, v208, vcc
	v_cmp_lt_i32_e32 vcc, v157, v233
	v_cmp_gt_i32_e64 s[78:79], v157, v117
	s_or_b64 vcc, vcc, s[78:79]
	v_or_b32_e32 v157, 25, v156
	v_cndmask_b32_e32 v44, v44, v208, vcc
	v_cmp_lt_i32_e32 vcc, v157, v233
	v_cmp_gt_i32_e64 s[78:79], v157, v117
	s_or_b64 vcc, vcc, s[78:79]
	v_or_b32_e32 v157, 57, v156
	v_cndmask_b32_e32 v61, v61, v208, vcc
	v_cmp_lt_i32_e32 vcc, v157, v233
	v_cmp_gt_i32_e64 s[78:79], v157, v117
	s_or_b64 vcc, vcc, s[78:79]
	v_or_b32_e32 v157, 26, v156
	v_cndmask_b32_e32 v45, v45, v208, vcc
	v_cmp_lt_i32_e32 vcc, v157, v233
	v_cmp_gt_i32_e64 s[78:79], v157, v117
	s_or_b64 vcc, vcc, s[78:79]
	v_or_b32_e32 v157, 58, v156
	v_cndmask_b32_e32 v62, v62, v208, vcc
	v_cmp_lt_i32_e32 vcc, v157, v233
	v_cmp_gt_i32_e64 s[78:79], v157, v117
	s_or_b64 vcc, vcc, s[78:79]
	v_or_b32_e32 v157, 27, v156
	v_cndmask_b32_e32 v46, v46, v208, vcc
	v_cmp_lt_i32_e32 vcc, v157, v233
	v_cmp_gt_i32_e64 s[78:79], v157, v117
	s_or_b64 vcc, vcc, s[78:79]
	v_or_b32_e32 v156, 59, v156
	v_cndmask_b32_e32 v63, v63, v208, vcc
	v_cmp_lt_i32_e32 vcc, v156, v233
	v_cmp_gt_i32_e64 s[78:79], v156, v117
	s_or_b64 vcc, vcc, s[78:79]
	v_cndmask_b32_e32 v47, v47, v208, vcc
	s_branch .LBB0_121

.LBB0_143:
	v_add_u32_e32 v32, v114, v160
	v_ashrrev_i32_e32 v33, 31, v32
	v_lshlrev_b64 v[32:33], 12, v[32:33]
	v_lshl_add_u64 v[72:73], v[92:93], 0, v[32:33]
	global_load_dwordx4 v[32:35], v[72:73], off offset:2048
	global_load_dwordx4 v[64:67], v[72:73], off offset:2080
	global_load_dwordx4 v[68:71], v[72:73], off offset:2112
	global_load_dwordx4 v[94:97], v[72:73], off offset:2144
	v_lshlrev_b32_e32 v134, 6, v160
	s_movk_i32 s38, 0x800
	v_lshl_add_u64 v[76:77], v[134:135], 1, v[90:91]
	s_waitcnt vmcnt(3)
	v_mfma_f32_32x32x16_bf16 v[32:47], v[32:35], v[48:51], 0
	s_waitcnt vmcnt(2)
	v_mfma_f32_32x32x16_bf16 v[32:47], v[64:67], v[52:55], v[32:47]
	global_load_dwordx4 v[72:75], v[76:77], off
	global_load_dwordx4 v[64:67], v[76:77], off offset:1024
	s_waitcnt vmcnt(3)
	v_mfma_f32_32x32x16_bf16 v[32:47], v[68:71], v[56:59], v[32:47]
	v_add_co_u32_e64 v70, s[38:39], s38, v76
	s_nop 1
	v_addc_co_u32_e64 v71, s[38:39], 0, v77, s[38:39]
	global_load_dwordx4 v[76:79], v[70:71], off
	global_load_dwordx4 v[68:71], v[70:71], off offset:1024
	v_cmp_eq_u32_e64 s[38:39], v85, v160
	s_waitcnt vmcnt(4)
	v_mfma_f32_32x32x16_bf16 v[32:47], v[94:97], v[60:63], v[32:47]
	s_nop 11
	v_exp_f32_e32 v32, v32
	v_exp_f32_e32 v33, v33
	v_exp_f32_e32 v34, v34
	v_exp_f32_e32 v35, v35
	v_exp_f32_e32 v94, v36
	v_exp_f32_e32 v95, v37
	v_exp_f32_e32 v38, v38
	v_exp_f32_e32 v39, v39
	v_exp_f32_e32 v40, v40
	v_exp_f32_e32 v41, v41
	v_exp_f32_e32 v42, v42
	v_exp_f32_e32 v43, v43
	v_exp_f32_e32 v96, v44
	v_exp_f32_e32 v97, v45
	v_exp_f32_e32 v46, v46
	v_exp_f32_e32 v47, v47
	v_min_f32_e32 v36, 0x7149f2ca, v32
	v_min_f32_e32 v37, 0x7149f2ca, v33
	v_min_f32_e32 v32, 0x7149f2ca, v34
	v_min_f32_e32 v100, 0x7149f2ca, v35
	v_min_f32_e32 v44, 0x7149f2ca, v94
	v_min_f32_e32 v45, 0x7149f2ca, v95
	v_min_f32_e32 v38, 0x7149f2ca, v38
	v_min_f32_e32 v104, 0x7149f2ca, v39
	v_min_f32_e32 v116, 0x7149f2ca, v40
	v_min_f32_e32 v117, 0x7149f2ca, v41
	v_min_f32_e32 v40, 0x7149f2ca, v42
	v_min_f32_e32 v42, 0x7149f2ca, v43
	v_min_f32_e32 v124, 0x7149f2ca, v96
	v_min_f32_e32 v125, 0x7149f2ca, v97
	v_min_f32_e32 v106, 0x7149f2ca, v46
	v_min_f32_e32 v108, 0x7149f2ca, v47
	v_add_f32_e32 v33, 1.0, v36
	v_add_f32_e32 v34, 1.0, v37
	v_add_f32_e32 v35, 1.0, v32
	v_add_f32_e32 v39, 1.0, v100
	v_add_f32_e32 v41, 1.0, v44
	v_add_f32_e32 v94, 1.0, v45
	v_add_f32_e32 v95, 1.0, v38
	v_add_f32_e32 v98, 1.0, v104
	v_add_f32_e32 v99, 1.0, v116
	v_add_f32_e32 v103, 1.0, v117
	v_add_f32_e32 v107, 1.0, v40
	v_add_f32_e32 v109, 1.0, v42
	v_add_f32_e32 v118, 1.0, v124
	v_add_f32_e32 v119, 1.0, v125
	v_add_f32_e32 v120, 1.0, v106
	v_add_f32_e32 v121, 1.0, v108
	v_rcp_f32_e32 v46, v33
	v_rcp_f32_e32 v47, v34
	v_rcp_f32_e32 v101, v35
	v_rcp_f32_e32 v43, v39
	v_rcp_f32_e32 v96, v41
	v_rcp_f32_e32 v97, v94
	v_rcp_f32_e32 v105, v95
	v_rcp_f32_e32 v41, v98
	v_rcp_f32_e32 v102, v99
	v_rcp_f32_e32 v103, v103
	v_rcp_f32_e32 v107, v107
	v_rcp_f32_e32 v39, v109
	v_rcp_f32_e32 v34, v118
	v_rcp_f32_e32 v35, v119
	v_rcp_f32_e32 v109, v120
	v_rcp_f32_e32 v33, v121
	v_pk_mul_f32 v[98:99], v[36:37], v[46:47]
	v_mul_f32_e32 v123, v32, v101
	v_mul_f32_e32 v122, v100, v43
	v_pk_mul_f32 v[94:95], v[44:45], v[96:97]
	v_mul_f32_e32 v120, v38, v105
	v_mul_f32_e32 v121, v104, v41
	v_pk_mul_f32 v[44:45], v[116:117], v[102:103]
	v_mul_f32_e32 v118, v40, v107
	v_mul_f32_e32 v119, v42, v39
	v_pk_mul_f32 v[36:37], v[124:125], v[34:35]
	v_mul_f32_e32 v116, v106, v109
	v_mul_f32_e32 v117, v108, v33
	s_and_saveexec_b64 s[44:45], s[38:39]
	s_cbranch_execz .LBB0_142
	v_cndmask_b32_e64 v46, 1.0, v46, s[4:5]
	v_cndmask_b32_e64 v47, 1.0, v47, s[6:7]
	v_cndmask_b32_e64 v99, 0, v99, s[6:7]
	v_cndmask_b32_e64 v98, 0, v98, s[4:5]
	v_cndmask_b32_e64 v101, 1.0, v101, s[8:9]
	v_cndmask_b32_e64 v123, 0, v123, s[8:9]
	v_cndmask_b32_e64 v43, 1.0, v43, s[10:11]
	v_cndmask_b32_e64 v122, 0, v122, s[10:11]
	v_cndmask_b32_e64 v96, 1.0, v96, s[14:15]
	v_cndmask_b32_e64 v97, 1.0, v97, s[12:13]
	v_cndmask_b32_e64 v95, 0, v95, s[12:13]
	v_cndmask_b32_e64 v94, 0, v94, s[14:15]
	v_cndmask_b32_e64 v105, 1.0, v105, s[16:17]
	v_cndmask_b32_e64 v120, 0, v120, s[16:17]
	v_cndmask_b32_e64 v41, 1.0, v41, s[18:19]
	v_cndmask_b32_e64 v121, 0, v121, s[18:19]
	v_cndmask_b32_e64 v102, 1.0, v102, s[22:23]
	v_cndmask_b32_e64 v103, 1.0, v103, s[20:21]
	v_cndmask_b32_e64 v45, 0, v45, s[20:21]
	v_cndmask_b32_e64 v44, 0, v44, s[22:23]
	v_cndmask_b32_e64 v107, 1.0, v107, s[24:25]
	v_cndmask_b32_e64 v118, 0, v118, s[24:25]
	v_cndmask_b32_e64 v39, 1.0, v39, s[26:27]
	v_cndmask_b32_e64 v119, 0, v119, s[26:27]
	v_cndmask_b32_e64 v34, 1.0, v34, s[30:31]
	v_cndmask_b32_e64 v35, 1.0, v35, s[28:29]
	v_cndmask_b32_e64 v37, 0, v37, s[28:29]
	v_cndmask_b32_e64 v36, 0, v36, s[30:31]
	v_cndmask_b32_e64 v109, 1.0, v109, s[34:35]
	v_cndmask_b32_e64 v116, 0, v116, s[34:35]
	v_cndmask_b32_e64 v33, 1.0, v33, s[36:37]
	v_cndmask_b32_e64 v117, 0, v117, s[36:37]
	s_branch .LBB0_142
	s_nop 0
	s_nop 0
	s_nop 0
	s_nop 0
	s_nop 0
	s_nop 0
	s_nop 0
	s_nop 0
	s_nop 0
	s_nop 0
	s_nop 0
	s_nop 0
	s_nop 0
	s_nop 0
	s_nop 0
	s_nop 0
	s_nop 0
	s_nop 0
.LBB0_145:
	v_readlane_b32 s44, v253, 54
	s_movk_i32 s30, 0x1600
	s_movk_i32 s31, 0x5800
	s_movk_i32 s34, 0x104
	s_mov_b32 s36, 0x60000
	s_mov_b32 s37, 0x40000
	s_mov_b32 s38, 0x20000
	s_mov_b32 s35, 0x18000
	s_mov_b32 s39, 0x8000
	s_movk_i32 s40, 0x3fff
	v_readlane_b32 s45, v253, 55
	v_readlane_b32 s46, v253, 56
	v_readlane_b32 s47, v253, 57
	v_readlane_b32 s48, v253, 58
	v_readlane_b32 s49, v253, 59
	v_readlane_b32 s50, v253, 60
	v_readlane_b32 s51, v253, 61
	s_mov_b64 s[26:27], s[52:53]
	s_mov_b64 s[24:25], s[60:61]
	s_mov_b32 s29, s58
	s_mov_b64 s[22:23], s[62:63]
	s_mov_b64 s[42:43], 0
